# v47: v46 + prologue pass-1 load pipelining + K-loop bookkeeping hoisted into the last MFMA segment (all previously validated edits stacked)
# baseline (speedup 1.0000x reference)
.Lrb_skip_230:
.LBB0_230:
	s_add_u32 s98, s0, 0xfff00000
	s_addc_u32 s99, s1, -1
	s_add_u32 s28, s0, 0xfff00080
	s_addc_u32 s29, s1, -1
	s_add_i32 s51, 0, 0x10000
	s_cmp_eq_u32 s50, 60
	s_cselect_b32 s31, s34, s29
	s_cselect_b32 s30, s35, s28
	s_cselect_b32 s29, s27, s43
	s_cselect_b32 s28, s40, s41
	s_add_i32 s77, 0, 0x14000
.Lkb_230:
	v_add_u32_e32 v0, s51, v179
	ds_read_b128 v[130:133], v0
	ds_read_b128 v[134:137], v0 offset:1024
	ds_read_b128 v[138:141], v0 offset:2048
	ds_read_b128 v[142:145], v0 offset:3072
	v_add_u32_e32 v0, s77, v179
	ds_read_b128 v[146:149], v0
	ds_read_b128 v[150:153], v0 offset:1024
	ds_read_b128 v[154:157], v0 offset:2048
	ds_read_b128 v[158:161], v0 offset:3072
	s_mov_b32 m0, s54
	ds_read_b128 v[174:177], v192
	ds_read_b128 v[180:183], v192 offset:1024
	ds_read_b128 v[184:187], v192 offset:2048
	ds_read_b128 v[188:191], v192 offset:3072
	ds_read_b128 v[200:203], v192 offset:4096
	ds_read_b128 v[204:207], v192 offset:5120
	ds_read_b128 v[208:211], v192 offset:6144
	ds_read_b128 v[212:215], v192 offset:7168
	global_load_lds_dwordx4 v168, s[98:99]
	s_mov_b32 m0, s55
	s_nop 0
	global_load_lds_dwordx4 v164, s[98:99]
	s_add_i32 m0, s14, 0xc000
	s_nop 0
	global_load_lds_dwordx4 v170, s[0:1]
	s_add_i32 m0, s14, 0xe000
	s_nop 0
	global_load_lds_dwordx4 v172, s[0:1]
	s_waitcnt vmcnt(8)
	s_waitcnt lgkmcnt(0)
	s_barrier
	v_mfma_f32_16x16x32_bf16 v[126:129], v[130:133], v[174:177], v[126:129]
	v_mfma_f32_16x16x32_bf16 v[126:129], v[134:137], v[180:183], v[126:129]
	v_mfma_f32_16x16x32_bf16 v[110:113], v[130:133], v[184:187], v[110:113]
	v_mfma_f32_16x16x32_bf16 v[110:113], v[134:137], v[188:191], v[110:113]
	v_mfma_f32_16x16x32_bf16 v[94:97], v[130:133], v[200:203], v[94:97]
	v_mfma_f32_16x16x32_bf16 v[94:97], v[134:137], v[204:207], v[94:97]
	v_mfma_f32_16x16x32_bf16 v[78:81], v[130:133], v[208:211], v[78:81]
	v_mfma_f32_16x16x32_bf16 v[78:81], v[134:137], v[212:215], v[78:81]
	v_mfma_f32_16x16x32_bf16 v[122:125], v[138:141], v[174:177], v[122:125]
	v_mfma_f32_16x16x32_bf16 v[122:125], v[142:145], v[180:183], v[122:125]
	v_mfma_f32_16x16x32_bf16 v[106:109], v[138:141], v[184:187], v[106:109]
	v_mfma_f32_16x16x32_bf16 v[106:109], v[142:145], v[188:191], v[106:109]
	v_mfma_f32_16x16x32_bf16 v[90:93], v[138:141], v[200:203], v[90:93]
	v_mfma_f32_16x16x32_bf16 v[90:93], v[142:145], v[204:207], v[90:93]
	v_mfma_f32_16x16x32_bf16 v[74:77], v[138:141], v[208:211], v[74:77]
	v_mfma_f32_16x16x32_bf16 v[74:77], v[142:145], v[212:215], v[74:77]
	v_mfma_f32_16x16x32_bf16 v[118:121], v[146:149], v[174:177], v[118:121]
	v_mfma_f32_16x16x32_bf16 v[118:121], v[150:153], v[180:183], v[118:121]
	v_mfma_f32_16x16x32_bf16 v[102:105], v[146:149], v[184:187], v[102:105]
	v_mfma_f32_16x16x32_bf16 v[102:105], v[150:153], v[188:191], v[102:105]
	v_mfma_f32_16x16x32_bf16 v[86:89], v[146:149], v[200:203], v[86:89]
	v_mfma_f32_16x16x32_bf16 v[86:89], v[150:153], v[204:207], v[86:89]
	v_mfma_f32_16x16x32_bf16 v[70:73], v[146:149], v[208:211], v[70:73]
	v_mfma_f32_16x16x32_bf16 v[70:73], v[150:153], v[212:215], v[70:73]
	v_mfma_f32_16x16x32_bf16 v[114:117], v[154:157], v[174:177], v[114:117]
	v_mfma_f32_16x16x32_bf16 v[114:117], v[158:161], v[180:183], v[114:117]
	v_mfma_f32_16x16x32_bf16 v[98:101], v[154:157], v[184:187], v[98:101]
	v_mfma_f32_16x16x32_bf16 v[98:101], v[158:161], v[188:191], v[98:101]
	v_mfma_f32_16x16x32_bf16 v[82:85], v[154:157], v[200:203], v[82:85]
	v_mfma_f32_16x16x32_bf16 v[82:85], v[158:161], v[204:207], v[82:85]
	v_mfma_f32_16x16x32_bf16 v[66:69], v[154:157], v[208:211], v[66:69]
	v_mfma_f32_16x16x32_bf16 v[66:69], v[158:161], v[212:215], v[66:69]
	s_barrier
	s_add_i32 s51, s51, s9
	s_mov_b32 m0, s51
	ds_read_b128 v[174:177], v192 offset:16384
	ds_read_b128 v[180:183], v192 offset:17408
	ds_read_b128 v[184:187], v192 offset:18432
	ds_read_b128 v[188:191], v192 offset:19456
	ds_read_b128 v[200:203], v192 offset:20480
	ds_read_b128 v[204:207], v192 offset:21504
	ds_read_b128 v[208:211], v192 offset:22528
	ds_read_b128 v[212:215], v192 offset:23552
	global_load_lds_dwordx4 v166, s[28:29]
	s_add_i32 m0, s51, 0x2000
	s_add_u32 s80, s28, 0x100000
	s_addc_u32 s81, s29, 0
	s_add_i32 s51, s77, s9
	global_load_lds_dwordx4 v162, s[28:29]
	s_mov_b32 m0, s51
	s_nop 0
	global_load_lds_dwordx4 v166, s[80:81]
	s_add_i32 m0, s51, 0x2000
	s_nop 0
	global_load_lds_dwordx4 v162, s[80:81]
	s_waitcnt vmcnt(6)
	s_waitcnt lgkmcnt(0)
	s_barrier
	v_mfma_f32_16x16x32_bf16 v[62:65], v[130:133], v[174:177], v[62:65]
	v_mfma_f32_16x16x32_bf16 v[62:65], v[134:137], v[180:183], v[62:65]
	v_mfma_f32_16x16x32_bf16 v[46:49], v[130:133], v[184:187], v[46:49]
	v_mfma_f32_16x16x32_bf16 v[46:49], v[134:137], v[188:191], v[46:49]
	v_mfma_f32_16x16x32_bf16 v[30:33], v[130:133], v[200:203], v[30:33]
	v_mfma_f32_16x16x32_bf16 v[30:33], v[134:137], v[204:207], v[30:33]
	v_mfma_f32_16x16x32_bf16 v[14:17], v[130:133], v[208:211], v[14:17]
	v_mfma_f32_16x16x32_bf16 v[14:17], v[134:137], v[212:215], v[14:17]
	v_mfma_f32_16x16x32_bf16 v[58:61], v[138:141], v[174:177], v[58:61]
	v_mfma_f32_16x16x32_bf16 v[58:61], v[142:145], v[180:183], v[58:61]
	v_mfma_f32_16x16x32_bf16 v[42:45], v[138:141], v[184:187], v[42:45]
	v_mfma_f32_16x16x32_bf16 v[42:45], v[142:145], v[188:191], v[42:45]
	v_mfma_f32_16x16x32_bf16 v[26:29], v[138:141], v[200:203], v[26:29]
	v_mfma_f32_16x16x32_bf16 v[26:29], v[142:145], v[204:207], v[26:29]
	v_mfma_f32_16x16x32_bf16 v[10:13], v[138:141], v[208:211], v[10:13]
	v_mfma_f32_16x16x32_bf16 v[10:13], v[142:145], v[212:215], v[10:13]
	v_mfma_f32_16x16x32_bf16 v[54:57], v[146:149], v[174:177], v[54:57]
	v_mfma_f32_16x16x32_bf16 v[54:57], v[150:153], v[180:183], v[54:57]
	v_mfma_f32_16x16x32_bf16 v[38:41], v[146:149], v[184:187], v[38:41]
	v_mfma_f32_16x16x32_bf16 v[38:41], v[150:153], v[188:191], v[38:41]
	v_mfma_f32_16x16x32_bf16 v[22:25], v[146:149], v[200:203], v[22:25]
	v_mfma_f32_16x16x32_bf16 v[22:25], v[150:153], v[204:207], v[22:25]
	v_mfma_f32_16x16x32_bf16 v[6:9], v[146:149], v[208:211], v[6:9]
	v_mfma_f32_16x16x32_bf16 v[6:9], v[150:153], v[212:215], v[6:9]
	v_mfma_f32_16x16x32_bf16 v[50:53], v[154:157], v[174:177], v[50:53]
	v_mfma_f32_16x16x32_bf16 v[50:53], v[158:161], v[180:183], v[50:53]
	v_mfma_f32_16x16x32_bf16 v[34:37], v[154:157], v[184:187], v[34:37]
	v_mfma_f32_16x16x32_bf16 v[34:37], v[158:161], v[188:191], v[34:37]
	v_mfma_f32_16x16x32_bf16 v[18:21], v[154:157], v[200:203], v[18:21]
	v_mfma_f32_16x16x32_bf16 v[18:21], v[158:161], v[204:207], v[18:21]
	v_mfma_f32_16x16x32_bf16 v[2:5], v[154:157], v[208:211], v[2:5]
	v_mfma_f32_16x16x32_bf16 v[2:5], v[158:161], v[212:215], v[2:5]
	s_barrier
	s_add_i32 s51, 0, 0x18000
	v_add_u32_e32 v0, s51, v179
	s_add_i32 s77, 0, 0x1c000
	ds_read_b128 v[130:133], v0
	ds_read_b128 v[134:137], v0 offset:1024
	ds_read_b128 v[138:141], v0 offset:2048
	ds_read_b128 v[142:145], v0 offset:3072
	v_add_u32_e32 v0, s77, v179
	ds_read_b128 v[146:149], v0
	ds_read_b128 v[150:153], v0 offset:1024
	ds_read_b128 v[154:157], v0 offset:2048
	ds_read_b128 v[158:161], v0 offset:3072
	s_mov_b32 m0, s14
	ds_read_b128 v[174:177], v192 offset:32768
	ds_read_b128 v[180:183], v192 offset:33792
	ds_read_b128 v[184:187], v192 offset:34816
	ds_read_b128 v[188:191], v192 offset:35840
	ds_read_b128 v[200:203], v192 offset:36864
	ds_read_b128 v[204:207], v192 offset:37888
	ds_read_b128 v[208:211], v192 offset:38912
	ds_read_b128 v[212:215], v192 offset:39936
	global_load_lds_dwordx4 v168, s[30:31]
	s_mov_b32 m0, s15
	s_nop 0
	global_load_lds_dwordx4 v164, s[30:31]
	s_add_u32 s30, s30, 0x100000
	s_addc_u32 s31, s31, 0
	s_mov_b32 m0, s52
	s_nop 0
	global_load_lds_dwordx4 v168, s[30:31]
	s_mov_b32 m0, s53
	s_nop 0
	global_load_lds_dwordx4 v164, s[30:31]
	s_waitcnt vmcnt(8)
	s_waitcnt lgkmcnt(0)
	s_barrier
	v_mfma_f32_16x16x32_bf16 v[126:129], v[130:133], v[174:177], v[126:129]
	v_mfma_f32_16x16x32_bf16 v[126:129], v[134:137], v[180:183], v[126:129]
	v_mfma_f32_16x16x32_bf16 v[110:113], v[130:133], v[184:187], v[110:113]
	v_mfma_f32_16x16x32_bf16 v[110:113], v[134:137], v[188:191], v[110:113]
	v_mfma_f32_16x16x32_bf16 v[94:97], v[130:133], v[200:203], v[94:97]
	v_mfma_f32_16x16x32_bf16 v[94:97], v[134:137], v[204:207], v[94:97]
	v_mfma_f32_16x16x32_bf16 v[78:81], v[130:133], v[208:211], v[78:81]
	v_mfma_f32_16x16x32_bf16 v[78:81], v[134:137], v[212:215], v[78:81]
	v_mfma_f32_16x16x32_bf16 v[122:125], v[138:141], v[174:177], v[122:125]
	v_mfma_f32_16x16x32_bf16 v[122:125], v[142:145], v[180:183], v[122:125]
	v_mfma_f32_16x16x32_bf16 v[106:109], v[138:141], v[184:187], v[106:109]
	v_mfma_f32_16x16x32_bf16 v[106:109], v[142:145], v[188:191], v[106:109]
	v_mfma_f32_16x16x32_bf16 v[90:93], v[138:141], v[200:203], v[90:93]
	v_mfma_f32_16x16x32_bf16 v[90:93], v[142:145], v[204:207], v[90:93]
	v_mfma_f32_16x16x32_bf16 v[74:77], v[138:141], v[208:211], v[74:77]
	v_mfma_f32_16x16x32_bf16 v[74:77], v[142:145], v[212:215], v[74:77]
	v_mfma_f32_16x16x32_bf16 v[118:121], v[146:149], v[174:177], v[118:121]
	v_mfma_f32_16x16x32_bf16 v[118:121], v[150:153], v[180:183], v[118:121]
	v_mfma_f32_16x16x32_bf16 v[102:105], v[146:149], v[184:187], v[102:105]
	v_mfma_f32_16x16x32_bf16 v[102:105], v[150:153], v[188:191], v[102:105]
	v_mfma_f32_16x16x32_bf16 v[86:89], v[146:149], v[200:203], v[86:89]
	v_mfma_f32_16x16x32_bf16 v[86:89], v[150:153], v[204:207], v[86:89]
	v_mfma_f32_16x16x32_bf16 v[70:73], v[146:149], v[208:211], v[70:73]
	v_mfma_f32_16x16x32_bf16 v[70:73], v[150:153], v[212:215], v[70:73]
	v_mfma_f32_16x16x32_bf16 v[114:117], v[154:157], v[174:177], v[114:117]
	v_mfma_f32_16x16x32_bf16 v[114:117], v[158:161], v[180:183], v[114:117]
	v_mfma_f32_16x16x32_bf16 v[98:101], v[154:157], v[184:187], v[98:101]
	v_mfma_f32_16x16x32_bf16 v[98:101], v[158:161], v[188:191], v[98:101]
	v_mfma_f32_16x16x32_bf16 v[82:85], v[154:157], v[200:203], v[82:85]
	v_mfma_f32_16x16x32_bf16 v[82:85], v[158:161], v[204:207], v[82:85]
	v_mfma_f32_16x16x32_bf16 v[66:69], v[154:157], v[208:211], v[66:69]
	v_mfma_f32_16x16x32_bf16 v[66:69], v[158:161], v[212:215], v[66:69]
	s_barrier
	s_add_u32 s98, s28, 0x80
	s_addc_u32 s99, s29, 0
	s_add_i32 s30, s51, s9
	s_mov_b32 m0, s30
	ds_read_b128 v[174:177], v192 offset:49152
	ds_read_b128 v[180:183], v192 offset:50176
	ds_read_b128 v[184:187], v192 offset:51200
	ds_read_b128 v[188:191], v192 offset:52224
	ds_read_b128 v[200:203], v192 offset:53248
	ds_read_b128 v[204:207], v192 offset:54272
	ds_read_b128 v[208:211], v192 offset:55296
	ds_read_b128 v[212:215], v192 offset:56320
	global_load_lds_dwordx4 v166, s[98:99]
	s_add_i32 m0, s30, 0x2000
	s_add_u32 s28, s28, 0x100080
	s_addc_u32 s29, s29, 0
	s_add_i32 s30, s77, s9
	global_load_lds_dwordx4 v162, s[98:99]
	s_mov_b32 m0, s30
	s_nop 0
	global_load_lds_dwordx4 v166, s[28:29]
	s_add_i32 m0, s30, 0x2000
	s_nop 0
	global_load_lds_dwordx4 v162, s[28:29]
	s_waitcnt vmcnt(6)
	s_waitcnt lgkmcnt(0)
	s_barrier
	v_mfma_f32_16x16x32_bf16 v[62:65], v[130:133], v[174:177], v[62:65]
	v_mfma_f32_16x16x32_bf16 v[62:65], v[134:137], v[180:183], v[62:65]
	v_mfma_f32_16x16x32_bf16 v[46:49], v[130:133], v[184:187], v[46:49]
	v_mfma_f32_16x16x32_bf16 v[46:49], v[134:137], v[188:191], v[46:49]
	v_mfma_f32_16x16x32_bf16 v[30:33], v[130:133], v[200:203], v[30:33]
	v_mfma_f32_16x16x32_bf16 v[30:33], v[134:137], v[204:207], v[30:33]
	v_mfma_f32_16x16x32_bf16 v[14:17], v[130:133], v[208:211], v[14:17]
	v_mfma_f32_16x16x32_bf16 v[14:17], v[134:137], v[212:215], v[14:17]
	v_mfma_f32_16x16x32_bf16 v[58:61], v[138:141], v[174:177], v[58:61]
	v_mfma_f32_16x16x32_bf16 v[58:61], v[142:145], v[180:183], v[58:61]
	v_mfma_f32_16x16x32_bf16 v[42:45], v[138:141], v[184:187], v[42:45]
	v_mfma_f32_16x16x32_bf16 v[42:45], v[142:145], v[188:191], v[42:45]
	s_add_i32 s50, s50, 2
	v_mfma_f32_16x16x32_bf16 v[26:29], v[138:141], v[200:203], v[26:29]
	v_mfma_f32_16x16x32_bf16 v[26:29], v[142:145], v[204:207], v[26:29]
	s_add_u32 s0, s0, 0x100
	s_addc_u32 s1, s1, 0
	v_mfma_f32_16x16x32_bf16 v[10:13], v[138:141], v[208:211], v[10:13]
	v_mfma_f32_16x16x32_bf16 v[10:13], v[142:145], v[212:215], v[10:13]
	s_add_u32 s41, s41, 0x100
	s_addc_u32 s43, s43, 0
	v_mfma_f32_16x16x32_bf16 v[54:57], v[146:149], v[174:177], v[54:57]
	v_mfma_f32_16x16x32_bf16 v[54:57], v[150:153], v[180:183], v[54:57]
	s_add_u32 s98, s0, 0xfff00000
	s_addc_u32 s99, s1, -1
	v_mfma_f32_16x16x32_bf16 v[38:41], v[146:149], v[184:187], v[38:41]
	v_mfma_f32_16x16x32_bf16 v[38:41], v[150:153], v[188:191], v[38:41]
	s_add_u32 s28, s0, 0xfff00080
	s_addc_u32 s29, s1, -1
	v_mfma_f32_16x16x32_bf16 v[22:25], v[146:149], v[200:203], v[22:25]
	v_mfma_f32_16x16x32_bf16 v[22:25], v[150:153], v[204:207], v[22:25]
	s_add_i32 s51, 0, 0x10000
	v_mfma_f32_16x16x32_bf16 v[6:9], v[146:149], v[208:211], v[6:9]
	v_mfma_f32_16x16x32_bf16 v[6:9], v[150:153], v[212:215], v[6:9]
	s_cmp_eq_u32 s50, 60
	s_cselect_b32 s31, s34, s29
	s_cselect_b32 s30, s35, s28
	s_cselect_b32 s29, s27, s43
	s_cselect_b32 s28, s40, s41
	v_mfma_f32_16x16x32_bf16 v[50:53], v[154:157], v[174:177], v[50:53]
	v_mfma_f32_16x16x32_bf16 v[50:53], v[158:161], v[180:183], v[50:53]
	s_add_i32 s77, 0, 0x14000
	v_mfma_f32_16x16x32_bf16 v[34:37], v[154:157], v[184:187], v[34:37]
	v_mfma_f32_16x16x32_bf16 v[34:37], v[158:161], v[188:191], v[34:37]
	s_cmp_gt_u32 s50, 61
	v_mfma_f32_16x16x32_bf16 v[18:21], v[154:157], v[200:203], v[18:21]
	v_mfma_f32_16x16x32_bf16 v[18:21], v[158:161], v[204:207], v[18:21]
	v_mfma_f32_16x16x32_bf16 v[2:5], v[154:157], v[208:211], v[2:5]
	v_mfma_f32_16x16x32_bf16 v[2:5], v[158:161], v[212:215], v[2:5]
	s_barrier
	s_cbranch_scc0 .Lkb_230
	s_and_b64 vcc, exec, s[22:23]
	s_cbranch_vccz .LBB0_233
	s_barrier

.Lrb_skip_300:
.LBB0_300:
	s_add_u32 s100, s0, 0xfff80000
	s_addc_u32 s101, s1, -1
	s_add_u32 s28, s0, 0xfff80080
	s_addc_u32 s29, s1, -1
	s_add_i32 s42, 0, 0x10000
	s_cmp_eq_u32 s41, 28
	s_cselect_b32 s31, s18, s29
	s_cselect_b32 s30, s19, s28
	s_cselect_b32 s29, s27, s40
	s_cselect_b32 s28, s34, s35
	s_add_i32 s49, 0, 0x14000

.Lspf_j2:
	s_waitcnt lgkmcnt(0)
	s_barrier
	v_mfma_i32_16x16x64_i8 v[142:145], v[34:37], v[174:177], v[142:145]
	v_mfma_i32_16x16x64_i8 v[142:145], v[38:41], v[178:181], v[142:145]
	v_mfma_i32_16x16x64_i8 v[134:137], v[34:37], v[182:185], v[134:137]
	v_mfma_i32_16x16x64_i8 v[134:137], v[38:41], v[186:189], v[134:137]
	v_mfma_i32_16x16x64_i8 v[122:125], v[34:37], v[190:193], v[122:125]
	v_mfma_i32_16x16x64_i8 v[122:125], v[38:41], v[200:203], v[122:125]
	v_mfma_i32_16x16x64_i8 v[106:109], v[34:37], v[204:207], v[106:109]
	v_mfma_i32_16x16x64_i8 v[106:109], v[38:41], v[208:211], v[106:109]
	v_mfma_i32_16x16x64_i8 v[138:141], v[58:61], v[174:177], v[138:141]
	v_mfma_i32_16x16x64_i8 v[138:141], v[62:65], v[178:181], v[138:141]
	v_mfma_i32_16x16x64_i8 v[130:133], v[58:61], v[182:185], v[130:133]
	v_mfma_i32_16x16x64_i8 v[130:133], v[62:65], v[186:189], v[130:133]
	v_mfma_i32_16x16x64_i8 v[114:117], v[58:61], v[190:193], v[114:117]
	v_mfma_i32_16x16x64_i8 v[114:117], v[62:65], v[200:203], v[114:117]
	v_mfma_i32_16x16x64_i8 v[98:101], v[58:61], v[204:207], v[98:101]
	v_mfma_i32_16x16x64_i8 v[98:101], v[62:65], v[208:211], v[98:101]
	v_mfma_i32_16x16x64_i8 v[126:129], v[146:149], v[174:177], v[126:129]
	v_mfma_i32_16x16x64_i8 v[126:129], v[150:153], v[178:181], v[126:129]
	v_mfma_i32_16x16x64_i8 v[110:113], v[146:149], v[182:185], v[110:113]
	v_mfma_i32_16x16x64_i8 v[110:113], v[150:153], v[186:189], v[110:113]
	v_mfma_i32_16x16x64_i8 v[94:97], v[146:149], v[190:193], v[94:97]
	v_mfma_i32_16x16x64_i8 v[94:97], v[150:153], v[200:203], v[94:97]
	v_mfma_i32_16x16x64_i8 v[86:89], v[146:149], v[204:207], v[86:89]
	v_mfma_i32_16x16x64_i8 v[86:89], v[150:153], v[208:211], v[86:89]
	v_mfma_i32_16x16x64_i8 v[118:121], v[154:157], v[174:177], v[118:121]
	v_mfma_i32_16x16x64_i8 v[118:121], v[158:161], v[178:181], v[118:121]
	v_mfma_i32_16x16x64_i8 v[102:105], v[154:157], v[182:185], v[102:105]
	v_mfma_i32_16x16x64_i8 v[102:105], v[158:161], v[186:189], v[102:105]
	v_mfma_i32_16x16x64_i8 v[90:93], v[154:157], v[190:193], v[90:93]
	v_mfma_i32_16x16x64_i8 v[90:93], v[158:161], v[200:203], v[90:93]
	v_mfma_i32_16x16x64_i8 v[82:85], v[154:157], v[204:207], v[82:85]
	v_mfma_i32_16x16x64_i8 v[82:85], v[158:161], v[208:211], v[82:85]
	s_barrier
	s_add_i32 s30, s42, s81
	s_add_u32 s98, s28, 0x80
	s_addc_u32 s99, s29, 0
	s_mov_b32 m0, s30
	ds_read_b128 v[174:177], v250 offset:49152
	ds_read_b128 v[178:181], v250 offset:50176
	ds_read_b128 v[182:185], v250 offset:51200
	ds_read_b128 v[186:189], v250 offset:52224
	ds_read_b128 v[190:193], v250 offset:53248
	ds_read_b128 v[200:203], v250 offset:54272
	ds_read_b128 v[204:207], v250 offset:55296
	ds_read_b128 v[208:211], v250 offset:56320
	global_load_lds_dwordx4 v164, s[98:99]
	s_add_i32 m0, s30, 0x2000
	s_add_u32 s28, s28, 0x80080
	s_addc_u32 s29, s29, 0
	s_add_i32 s30, s43, s81
	global_load_lds_dwordx4 v168, s[98:99]
	s_mov_b32 m0, s30
	s_nop 0
	global_load_lds_dwordx4 v164, s[28:29]
	s_add_i32 m0, s30, 0x2000
	s_nop 0
	global_load_lds_dwordx4 v168, s[28:29]
	s_waitcnt vmcnt(6)
	s_waitcnt lgkmcnt(0)
	s_barrier
	v_mfma_i32_16x16x64_i8 v[78:81], v[34:37], v[174:177], v[78:81]
	v_mfma_i32_16x16x64_i8 v[78:81], v[38:41], v[178:181], v[78:81]
	v_mfma_i32_16x16x64_i8 v[70:73], v[34:37], v[182:185], v[70:73]
	v_mfma_i32_16x16x64_i8 v[70:73], v[38:41], v[186:189], v[70:73]
	v_mfma_i32_16x16x64_i8 v[54:57], v[34:37], v[190:193], v[54:57]
	v_mfma_i32_16x16x64_i8 v[54:57], v[38:41], v[200:203], v[54:57]
	v_mfma_i32_16x16x64_i8 v[2:5], v[34:37], v[204:207], v[2:5]
	v_mfma_i32_16x16x64_i8 v[38:41], v[38:41], v[208:211], v[2:5]
	v_mfma_i32_16x16x64_i8 v[74:77], v[58:61], v[174:177], v[74:77]
	v_mfma_i32_16x16x64_i8 v[74:77], v[62:65], v[178:181], v[74:77]
	v_mfma_i32_16x16x64_i8 v[66:69], v[58:61], v[182:185], v[66:69]
	v_mfma_i32_16x16x64_i8 v[66:69], v[62:65], v[186:189], v[66:69]
	s_add_i32 s41, s41, 2
	v_mfma_i32_16x16x64_i8 v[50:53], v[58:61], v[190:193], v[50:53]
	v_mfma_i32_16x16x64_i8 v[50:53], v[62:65], v[200:203], v[50:53]
	s_add_u32 s0, s0, 0x100
	s_addc_u32 s1, s1, 0
	v_mfma_i32_16x16x64_i8 v[2:5], v[58:61], v[204:207], v[6:9]
	v_mfma_i32_16x16x64_i8 v[34:37], v[62:65], v[208:211], v[2:5]
	s_add_u32 s35, s35, 0x100
	s_addc_u32 s40, s40, 0
	v_mfma_i32_16x16x64_i8 v[2:5], v[146:149], v[174:177], v[10:13]
	v_mfma_i32_16x16x64_i8 v[62:65], v[150:153], v[178:181], v[2:5]
	s_add_u32 s100, s0, 0xfff80000
	s_addc_u32 s101, s1, -1
	v_mfma_i32_16x16x64_i8 v[2:5], v[154:157], v[174:177], v[14:17]
	v_mfma_i32_16x16x64_i8 v[58:61], v[158:161], v[178:181], v[2:5]
	s_add_u32 s28, s0, 0xfff80080
	s_addc_u32 s29, s1, -1
	v_mfma_i32_16x16x64_i8 v[2:5], v[146:149], v[182:185], v[46:49]
	v_mfma_i32_16x16x64_i8 v[46:49], v[150:153], v[186:189], v[2:5]
	s_add_i32 s42, 0, 0x10000
	v_mfma_i32_16x16x64_i8 v[2:5], v[154:157], v[182:185], v[42:45]
	v_mfma_i32_16x16x64_i8 v[42:45], v[158:161], v[186:189], v[2:5]
	s_cmp_eq_u32 s41, 28
	s_cselect_b32 s31, s18, s29
	s_cselect_b32 s30, s19, s28
	s_cselect_b32 s29, s27, s40
	s_cselect_b32 s28, s34, s35
	v_mfma_i32_16x16x64_i8 v[2:5], v[146:149], v[190:193], v[30:33]
	v_mfma_i32_16x16x64_i8 v[30:33], v[150:153], v[200:203], v[2:5]
	s_add_i32 s49, 0, 0x14000
	v_mfma_i32_16x16x64_i8 v[2:5], v[154:157], v[190:193], v[26:29]
	v_mfma_i32_16x16x64_i8 v[26:29], v[158:161], v[200:203], v[2:5]
	s_cmp_gt_u32 s41, 29
	v_mfma_i32_16x16x64_i8 v[2:5], v[146:149], v[204:207], v[22:25]
	v_mfma_i32_16x16x64_i8 v[22:25], v[150:153], v[208:211], v[2:5]
	v_mfma_i32_16x16x64_i8 v[2:5], v[154:157], v[204:207], v[18:21]
	v_mfma_i32_16x16x64_i8 v[18:21], v[158:161], v[208:211], v[2:5]
	s_barrier
	s_cbranch_scc0 .Lkb_300

.Lrb_skip_577:
.LBB0_577:
	s_add_u32 s98, s30, 0xfff80000
	s_addc_u32 s99, s31, -1
	s_add_u32 s34, s30, 0xfff80080
	s_addc_u32 s35, s31, -1
	s_add_i32 s66, 0, 0x10000
	s_cmp_eq_u32 s57, 28
	s_cselect_b32 s43, s19, s35
	s_cselect_b32 s42, s23, s34
	s_cselect_b32 s35, s25, s56
	s_cselect_b32 s34, s54, s55
	s_add_i32 s73, 0, 0x14000
.Lkb_577:
	v_add_u32_e32 v0, s66, v228
	ds_read_b128 v[132:135], v0
	ds_read_b128 v[136:139], v0 offset:1024
	ds_read_b128 v[140:143], v0 offset:2048
	ds_read_b128 v[144:147], v0 offset:3072
	v_add_u32_e32 v0, s73, v228
	ds_read_b128 v[148:151], v0
	ds_read_b128 v[152:155], v0 offset:1024
	ds_read_b128 v[156:159], v0 offset:2048
	ds_read_b128 v[160:163], v0 offset:3072
	s_mov_b32 m0, s50
	ds_read_b128 v[164:167], v230
	ds_read_b128 v[168:171], v230 offset:1024
	ds_read_b128 v[172:175], v230 offset:2048
	ds_read_b128 v[176:179], v230 offset:3072
	ds_read_b128 v[180:183], v230 offset:4096
	ds_read_b128 v[184:187], v230 offset:5120
	ds_read_b128 v[188:191], v230 offset:6144
	ds_read_b128 v[192:195], v230 offset:7168
	global_load_lds_dwordx4 v206, s[98:99]
	s_mov_b32 m0, s51
	s_nop 0
	global_load_lds_dwordx4 v202, s[98:99]
	s_add_i32 m0, s46, 0xc000
	s_nop 0
	global_load_lds_dwordx4 v208, s[30:31]
	s_add_i32 m0, s46, 0xe000
	s_nop 0
	global_load_lds_dwordx4 v210, s[30:31]
	s_waitcnt vmcnt(8)
	s_waitcnt lgkmcnt(0)
	s_barrier
	v_mfma_f32_16x16x32_bf16 v[128:131], v[132:135], v[164:167], v[128:131]
	v_mfma_f32_16x16x32_bf16 v[128:131], v[136:139], v[168:171], v[128:131]
	v_mfma_f32_16x16x32_bf16 v[120:123], v[132:135], v[172:175], v[120:123]
	v_mfma_f32_16x16x32_bf16 v[120:123], v[136:139], v[176:179], v[120:123]
	v_mfma_f32_16x16x32_bf16 v[112:115], v[132:135], v[180:183], v[112:115]
	v_mfma_f32_16x16x32_bf16 v[112:115], v[136:139], v[184:187], v[112:115]
	v_mfma_f32_16x16x32_bf16 v[104:107], v[132:135], v[188:191], v[104:107]
	v_mfma_f32_16x16x32_bf16 v[104:107], v[136:139], v[192:195], v[104:107]
	v_mfma_f32_16x16x32_bf16 v[124:127], v[140:143], v[164:167], v[124:127]
	v_mfma_f32_16x16x32_bf16 v[124:127], v[144:147], v[168:171], v[124:127]
	v_mfma_f32_16x16x32_bf16 v[116:119], v[140:143], v[172:175], v[116:119]
	v_mfma_f32_16x16x32_bf16 v[116:119], v[144:147], v[176:179], v[116:119]
	v_mfma_f32_16x16x32_bf16 v[108:111], v[140:143], v[180:183], v[108:111]
	v_mfma_f32_16x16x32_bf16 v[108:111], v[144:147], v[184:187], v[108:111]
	v_mfma_f32_16x16x32_bf16 v[100:103], v[140:143], v[188:191], v[100:103]
	v_mfma_f32_16x16x32_bf16 v[100:103], v[144:147], v[192:195], v[100:103]
	v_mfma_f32_16x16x32_bf16 v[96:99], v[148:151], v[164:167], v[96:99]
	v_mfma_f32_16x16x32_bf16 v[96:99], v[152:155], v[168:171], v[96:99]
	v_mfma_f32_16x16x32_bf16 v[88:91], v[148:151], v[172:175], v[88:91]
	v_mfma_f32_16x16x32_bf16 v[88:91], v[152:155], v[176:179], v[88:91]
	v_mfma_f32_16x16x32_bf16 v[80:83], v[148:151], v[180:183], v[80:83]
	v_mfma_f32_16x16x32_bf16 v[80:83], v[152:155], v[184:187], v[80:83]
	v_mfma_f32_16x16x32_bf16 v[72:75], v[148:151], v[188:191], v[72:75]
	v_mfma_f32_16x16x32_bf16 v[72:75], v[152:155], v[192:195], v[72:75]
	v_mfma_f32_16x16x32_bf16 v[92:95], v[156:159], v[164:167], v[92:95]
	v_mfma_f32_16x16x32_bf16 v[92:95], v[160:163], v[168:171], v[92:95]
	v_mfma_f32_16x16x32_bf16 v[84:87], v[156:159], v[172:175], v[84:87]
	v_mfma_f32_16x16x32_bf16 v[84:87], v[160:163], v[176:179], v[84:87]
	v_mfma_f32_16x16x32_bf16 v[76:79], v[156:159], v[180:183], v[76:79]
	v_mfma_f32_16x16x32_bf16 v[76:79], v[160:163], v[184:187], v[76:79]
	v_mfma_f32_16x16x32_bf16 v[68:71], v[156:159], v[188:191], v[68:71]
	v_mfma_f32_16x16x32_bf16 v[68:71], v[160:163], v[192:195], v[68:71]
	s_barrier
	s_add_i32 s66, s66, s15
	s_mov_b32 m0, s66
	ds_read_b128 v[164:167], v230 offset:16384
	ds_read_b128 v[168:171], v230 offset:17408
	ds_read_b128 v[172:175], v230 offset:18432
	ds_read_b128 v[176:179], v230 offset:19456
	ds_read_b128 v[180:183], v230 offset:20480
	ds_read_b128 v[184:187], v230 offset:21504
	ds_read_b128 v[188:191], v230 offset:22528
	ds_read_b128 v[192:195], v230 offset:23552
	global_load_lds_dwordx4 v204, s[34:35]
	s_add_i32 m0, s66, 0x2000
	s_add_u32 s66, s34, 0x80000
	s_addc_u32 s67, s35, 0
	s_add_i32 s73, s73, s15
	global_load_lds_dwordx4 v200, s[34:35]
	s_mov_b32 m0, s73
	s_nop 0
	global_load_lds_dwordx4 v204, s[66:67]
	s_add_i32 m0, s73, 0x2000
	s_nop 0
	global_load_lds_dwordx4 v200, s[66:67]
	s_waitcnt vmcnt(6)
	s_waitcnt lgkmcnt(0)
	s_barrier
	v_mfma_f32_16x16x32_bf16 v[64:67], v[132:135], v[164:167], v[64:67]
	v_mfma_f32_16x16x32_bf16 v[64:67], v[136:139], v[168:171], v[64:67]
	v_mfma_f32_16x16x32_bf16 v[56:59], v[132:135], v[172:175], v[56:59]
	v_mfma_f32_16x16x32_bf16 v[56:59], v[136:139], v[176:179], v[56:59]
	v_mfma_f32_16x16x32_bf16 v[48:51], v[132:135], v[180:183], v[48:51]
	v_mfma_f32_16x16x32_bf16 v[48:51], v[136:139], v[184:187], v[48:51]
	v_mfma_f32_16x16x32_bf16 v[40:43], v[132:135], v[188:191], v[40:43]
	v_mfma_f32_16x16x32_bf16 v[40:43], v[136:139], v[192:195], v[40:43]
	v_mfma_f32_16x16x32_bf16 v[60:63], v[140:143], v[164:167], v[60:63]
	v_mfma_f32_16x16x32_bf16 v[60:63], v[144:147], v[168:171], v[60:63]
	v_mfma_f32_16x16x32_bf16 v[52:55], v[140:143], v[172:175], v[52:55]
	v_mfma_f32_16x16x32_bf16 v[52:55], v[144:147], v[176:179], v[52:55]
	v_mfma_f32_16x16x32_bf16 v[44:47], v[140:143], v[180:183], v[44:47]
	v_mfma_f32_16x16x32_bf16 v[44:47], v[144:147], v[184:187], v[44:47]
	v_mfma_f32_16x16x32_bf16 v[36:39], v[140:143], v[188:191], v[36:39]
	v_mfma_f32_16x16x32_bf16 v[36:39], v[144:147], v[192:195], v[36:39]
	v_mfma_f32_16x16x32_bf16 v[32:35], v[148:151], v[164:167], v[32:35]
	v_mfma_f32_16x16x32_bf16 v[32:35], v[152:155], v[168:171], v[32:35]
	v_mfma_f32_16x16x32_bf16 v[28:31], v[156:159], v[164:167], v[28:31]
	v_mfma_f32_16x16x32_bf16 v[28:31], v[160:163], v[168:171], v[28:31]
	v_mfma_f32_16x16x32_bf16 v[24:27], v[148:151], v[172:175], v[24:27]
	v_mfma_f32_16x16x32_bf16 v[24:27], v[152:155], v[176:179], v[24:27]
	v_mfma_f32_16x16x32_bf16 v[20:23], v[156:159], v[172:175], v[20:23]
	v_mfma_f32_16x16x32_bf16 v[20:23], v[160:163], v[176:179], v[20:23]
	v_mfma_f32_16x16x32_bf16 v[16:19], v[148:151], v[180:183], v[16:19]
	v_mfma_f32_16x16x32_bf16 v[16:19], v[152:155], v[184:187], v[16:19]
	v_mfma_f32_16x16x32_bf16 v[12:15], v[156:159], v[180:183], v[12:15]
	v_mfma_f32_16x16x32_bf16 v[12:15], v[160:163], v[184:187], v[12:15]
	v_mfma_f32_16x16x32_bf16 v[8:11], v[148:151], v[188:191], v[8:11]
	v_mfma_f32_16x16x32_bf16 v[8:11], v[152:155], v[192:195], v[8:11]
	v_mfma_f32_16x16x32_bf16 v[2:5], v[156:159], v[188:191], v[4:7]
	v_mfma_f32_16x16x32_bf16 v[2:5], v[160:163], v[192:195], v[2:5]
	s_barrier
	s_add_i32 s66, 0, 0x18000
	v_add_u32_e32 v0, s66, v228
	s_add_i32 s67, 0, 0x1c000
	ds_read_b128 v[132:135], v0
	ds_read_b128 v[136:139], v0 offset:1024
	ds_read_b128 v[140:143], v0 offset:2048
	ds_read_b128 v[144:147], v0 offset:3072
	v_add_u32_e32 v0, s67, v228
	ds_read_b128 v[148:151], v0
	ds_read_b128 v[152:155], v0 offset:1024
	ds_read_b128 v[156:159], v0 offset:2048
	ds_read_b128 v[160:163], v0 offset:3072
	s_mov_b32 m0, s46
	ds_read_b128 v[164:167], v230 offset:32768
	ds_read_b128 v[168:171], v230 offset:33792
	ds_read_b128 v[172:175], v230 offset:34816
	ds_read_b128 v[176:179], v230 offset:35840
	ds_read_b128 v[180:183], v230 offset:36864
	ds_read_b128 v[184:187], v230 offset:37888
	ds_read_b128 v[188:191], v230 offset:38912
	ds_read_b128 v[192:195], v230 offset:39936
	global_load_lds_dwordx4 v206, s[42:43]
	s_mov_b32 m0, s47
	s_nop 0
	global_load_lds_dwordx4 v202, s[42:43]
	s_add_u32 s42, s42, 0x80000
	s_addc_u32 s43, s43, 0
	s_mov_b32 m0, s48
	s_nop 0
	global_load_lds_dwordx4 v206, s[42:43]
	s_mov_b32 m0, s49
	s_nop 0
	global_load_lds_dwordx4 v202, s[42:43]
	s_waitcnt vmcnt(8)
	s_waitcnt lgkmcnt(0)
	s_barrier
	v_mfma_f32_16x16x32_bf16 v[128:131], v[132:135], v[164:167], v[128:131]
	v_mfma_f32_16x16x32_bf16 v[128:131], v[136:139], v[168:171], v[128:131]
	v_mfma_f32_16x16x32_bf16 v[120:123], v[132:135], v[172:175], v[120:123]
	v_mfma_f32_16x16x32_bf16 v[120:123], v[136:139], v[176:179], v[120:123]
	v_mfma_f32_16x16x32_bf16 v[112:115], v[132:135], v[180:183], v[112:115]
	v_mfma_f32_16x16x32_bf16 v[112:115], v[136:139], v[184:187], v[112:115]
	v_mfma_f32_16x16x32_bf16 v[104:107], v[132:135], v[188:191], v[104:107]
	v_mfma_f32_16x16x32_bf16 v[104:107], v[136:139], v[192:195], v[104:107]
	v_mfma_f32_16x16x32_bf16 v[124:127], v[140:143], v[164:167], v[124:127]
	v_mfma_f32_16x16x32_bf16 v[124:127], v[144:147], v[168:171], v[124:127]
	v_mfma_f32_16x16x32_bf16 v[116:119], v[140:143], v[172:175], v[116:119]
	v_mfma_f32_16x16x32_bf16 v[116:119], v[144:147], v[176:179], v[116:119]
	v_mfma_f32_16x16x32_bf16 v[108:111], v[140:143], v[180:183], v[108:111]
	v_mfma_f32_16x16x32_bf16 v[108:111], v[144:147], v[184:187], v[108:111]
	v_mfma_f32_16x16x32_bf16 v[100:103], v[140:143], v[188:191], v[100:103]
	v_mfma_f32_16x16x32_bf16 v[100:103], v[144:147], v[192:195], v[100:103]
	v_mfma_f32_16x16x32_bf16 v[96:99], v[148:151], v[164:167], v[96:99]
	v_mfma_f32_16x16x32_bf16 v[96:99], v[152:155], v[168:171], v[96:99]
	v_mfma_f32_16x16x32_bf16 v[88:91], v[148:151], v[172:175], v[88:91]
	v_mfma_f32_16x16x32_bf16 v[88:91], v[152:155], v[176:179], v[88:91]
	v_mfma_f32_16x16x32_bf16 v[80:83], v[148:151], v[180:183], v[80:83]
	v_mfma_f32_16x16x32_bf16 v[80:83], v[152:155], v[184:187], v[80:83]
	v_mfma_f32_16x16x32_bf16 v[72:75], v[148:151], v[188:191], v[72:75]
	v_mfma_f32_16x16x32_bf16 v[72:75], v[152:155], v[192:195], v[72:75]
	v_mfma_f32_16x16x32_bf16 v[92:95], v[156:159], v[164:167], v[92:95]
	v_mfma_f32_16x16x32_bf16 v[92:95], v[160:163], v[168:171], v[92:95]
	v_mfma_f32_16x16x32_bf16 v[84:87], v[156:159], v[172:175], v[84:87]
	v_mfma_f32_16x16x32_bf16 v[84:87], v[160:163], v[176:179], v[84:87]
	v_mfma_f32_16x16x32_bf16 v[76:79], v[156:159], v[180:183], v[76:79]
	v_mfma_f32_16x16x32_bf16 v[76:79], v[160:163], v[184:187], v[76:79]
	v_mfma_f32_16x16x32_bf16 v[68:71], v[156:159], v[188:191], v[68:71]
	v_mfma_f32_16x16x32_bf16 v[68:71], v[160:163], v[192:195], v[68:71]
	s_barrier
	s_add_i32 s42, s66, s15
	s_add_u32 s98, s34, 0x80
	s_addc_u32 s99, s35, 0
	s_mov_b32 m0, s42
	ds_read_b128 v[164:167], v230 offset:49152
	ds_read_b128 v[168:171], v230 offset:50176
	ds_read_b128 v[172:175], v230 offset:51200
	ds_read_b128 v[176:179], v230 offset:52224
	ds_read_b128 v[180:183], v230 offset:53248
	ds_read_b128 v[184:187], v230 offset:54272
	ds_read_b128 v[188:191], v230 offset:55296
	ds_read_b128 v[192:195], v230 offset:56320
	global_load_lds_dwordx4 v204, s[98:99]
	s_add_i32 m0, s42, 0x2000
	s_add_u32 s34, s34, 0x80080
	s_addc_u32 s35, s35, 0
	s_add_i32 s42, s67, s15
	global_load_lds_dwordx4 v200, s[98:99]
	s_mov_b32 m0, s42
	s_nop 0
	global_load_lds_dwordx4 v204, s[34:35]
	s_add_i32 m0, s42, 0x2000
	s_nop 0
	global_load_lds_dwordx4 v200, s[34:35]
	s_waitcnt vmcnt(6)
	s_waitcnt lgkmcnt(0)
	s_barrier
	v_mfma_f32_16x16x32_bf16 v[64:67], v[132:135], v[164:167], v[64:67]
	v_mfma_f32_16x16x32_bf16 v[64:67], v[136:139], v[168:171], v[64:67]
	v_mfma_f32_16x16x32_bf16 v[56:59], v[132:135], v[172:175], v[56:59]
	v_mfma_f32_16x16x32_bf16 v[56:59], v[136:139], v[176:179], v[56:59]
	v_mfma_f32_16x16x32_bf16 v[48:51], v[132:135], v[180:183], v[48:51]
	v_mfma_f32_16x16x32_bf16 v[48:51], v[136:139], v[184:187], v[48:51]
	v_mfma_f32_16x16x32_bf16 v[40:43], v[132:135], v[188:191], v[40:43]
	v_mfma_f32_16x16x32_bf16 v[40:43], v[136:139], v[192:195], v[40:43]
	v_mfma_f32_16x16x32_bf16 v[60:63], v[140:143], v[164:167], v[60:63]
	v_mfma_f32_16x16x32_bf16 v[60:63], v[144:147], v[168:171], v[60:63]
	v_mfma_f32_16x16x32_bf16 v[52:55], v[140:143], v[172:175], v[52:55]
	v_mfma_f32_16x16x32_bf16 v[52:55], v[144:147], v[176:179], v[52:55]
	s_add_i32 s57, s57, 2
	v_mfma_f32_16x16x32_bf16 v[44:47], v[140:143], v[180:183], v[44:47]
	v_mfma_f32_16x16x32_bf16 v[44:47], v[144:147], v[184:187], v[44:47]
	s_add_u32 s30, s30, 0x100
	s_addc_u32 s31, s31, 0
	v_mfma_f32_16x16x32_bf16 v[36:39], v[140:143], v[188:191], v[36:39]
	v_mfma_f32_16x16x32_bf16 v[36:39], v[144:147], v[192:195], v[36:39]
	s_add_u32 s55, s55, 0x100
	s_addc_u32 s56, s56, 0
	v_mfma_f32_16x16x32_bf16 v[32:35], v[148:151], v[164:167], v[32:35]
	v_mfma_f32_16x16x32_bf16 v[32:35], v[152:155], v[168:171], v[32:35]
	s_add_u32 s98, s30, 0xfff80000
	s_addc_u32 s99, s31, -1
	v_mfma_f32_16x16x32_bf16 v[28:31], v[156:159], v[164:167], v[28:31]
	v_mfma_f32_16x16x32_bf16 v[28:31], v[160:163], v[168:171], v[28:31]
	s_add_u32 s34, s30, 0xfff80080
	s_addc_u32 s35, s31, -1
	v_mfma_f32_16x16x32_bf16 v[24:27], v[148:151], v[172:175], v[24:27]
	v_mfma_f32_16x16x32_bf16 v[24:27], v[152:155], v[176:179], v[24:27]
	s_add_i32 s66, 0, 0x10000
	v_mfma_f32_16x16x32_bf16 v[20:23], v[156:159], v[172:175], v[20:23]
	v_mfma_f32_16x16x32_bf16 v[20:23], v[160:163], v[176:179], v[20:23]
	s_cmp_eq_u32 s57, 28
	s_cselect_b32 s43, s19, s35
	s_cselect_b32 s42, s23, s34
	s_cselect_b32 s35, s25, s56
	s_cselect_b32 s34, s54, s55
	v_mfma_f32_16x16x32_bf16 v[16:19], v[148:151], v[180:183], v[16:19]
	v_mfma_f32_16x16x32_bf16 v[16:19], v[152:155], v[184:187], v[16:19]
	s_add_i32 s73, 0, 0x14000
	v_mfma_f32_16x16x32_bf16 v[12:15], v[156:159], v[180:183], v[12:15]
	v_mfma_f32_16x16x32_bf16 v[12:15], v[160:163], v[184:187], v[12:15]
	s_cmp_gt_u32 s57, 29
	v_mfma_f32_16x16x32_bf16 v[6:9], v[148:151], v[188:191], v[8:11]
	v_mfma_f32_16x16x32_bf16 v[8:11], v[152:155], v[192:195], v[6:9]
	v_mfma_f32_16x16x32_bf16 v[2:5], v[156:159], v[188:191], v[2:5]
	v_mfma_f32_16x16x32_bf16 v[4:7], v[160:163], v[192:195], v[2:5]
	s_barrier
	s_cbranch_scc0 .Lkb_577
	s_and_b64 vcc, exec, s[20:21]
	s_cbranch_vccz .LBB0_580
	s_barrier

.Lkb_779:
	v_add_u32_e32 v114, s66, v157
	v_add_u32_e32 v156, s73, v157
	ds_read_b128 v[90:93], v114
	ds_read_b128 v[94:97], v114 offset:1024
	ds_read_b128 v[106:109], v114 offset:2048
	ds_read_b128 v[114:117], v114 offset:3072
	ds_read_b128 v[162:165], v156
	ds_read_b128 v[166:169], v156 offset:1024
	ds_read_b128 v[170:173], v156 offset:2048
	ds_read_b128 v[174:177], v156 offset:3072
	s_mov_b32 m0, s50
	ds_read_b128 v[178:181], v161
	ds_read_b128 v[182:185], v161 offset:1024
	ds_read_b128 v[186:189], v161 offset:2048
	ds_read_b128 v[190:193], v161 offset:3072
	ds_read_b128 v[200:203], v161 offset:4096
	ds_read_b128 v[204:207], v161 offset:5120
	ds_read_b128 v[208:211], v161 offset:6144
	ds_read_b128 v[212:215], v161 offset:7168
	global_load_lds_dwordx4 v150, s[98:99]
	s_mov_b32 m0, s51
	s_nop 0
	global_load_lds_dwordx4 v148, s[98:99]
	s_add_i32 m0, s14, 0xc000
	s_nop 0
	global_load_lds_dwordx4 v152, s[30:31]
	s_add_i32 m0, s14, 0xe000
	s_nop 0
	global_load_lds_dwordx4 v154, s[30:31]
	s_waitcnt vmcnt(8)
	s_waitcnt lgkmcnt(0)
	s_barrier
	v_mfma_i32_16x16x64_i8 v[142:145], v[90:93], v[178:181], v[142:145]
	v_mfma_i32_16x16x64_i8 v[142:145], v[94:97], v[182:185], v[142:145]
	v_mfma_i32_16x16x64_i8 v[126:129], v[90:93], v[186:189], v[126:129]
	v_mfma_i32_16x16x64_i8 v[126:129], v[94:97], v[190:193], v[126:129]
	v_mfma_i32_16x16x64_i8 v[102:105], v[90:93], v[200:203], v[102:105]
	v_mfma_i32_16x16x64_i8 v[102:105], v[94:97], v[204:207], v[102:105]
	v_mfma_i32_16x16x64_i8 v[78:81], v[90:93], v[208:211], v[78:81]
	v_mfma_i32_16x16x64_i8 v[78:81], v[94:97], v[212:215], v[78:81]
	v_mfma_i32_16x16x64_i8 v[138:141], v[106:109], v[178:181], v[138:141]
	v_mfma_i32_16x16x64_i8 v[138:141], v[114:117], v[182:185], v[138:141]
	v_mfma_i32_16x16x64_i8 v[122:125], v[106:109], v[186:189], v[122:125]
	v_mfma_i32_16x16x64_i8 v[122:125], v[114:117], v[190:193], v[122:125]
	v_mfma_i32_16x16x64_i8 v[98:101], v[106:109], v[200:203], v[98:101]
	v_mfma_i32_16x16x64_i8 v[98:101], v[114:117], v[204:207], v[98:101]
	v_mfma_i32_16x16x64_i8 v[74:77], v[106:109], v[208:211], v[74:77]
	v_mfma_i32_16x16x64_i8 v[74:77], v[114:117], v[212:215], v[74:77]
	v_mfma_i32_16x16x64_i8 v[134:137], v[162:165], v[178:181], v[134:137]
	v_mfma_i32_16x16x64_i8 v[134:137], v[166:169], v[182:185], v[134:137]
	v_mfma_i32_16x16x64_i8 v[118:121], v[162:165], v[186:189], v[118:121]
	v_mfma_i32_16x16x64_i8 v[118:121], v[166:169], v[190:193], v[118:121]
	v_mfma_i32_16x16x64_i8 v[86:89], v[162:165], v[200:203], v[86:89]
	v_mfma_i32_16x16x64_i8 v[86:89], v[166:169], v[204:207], v[86:89]
	v_mfma_i32_16x16x64_i8 v[70:73], v[162:165], v[208:211], v[70:73]
	v_mfma_i32_16x16x64_i8 v[70:73], v[166:169], v[212:215], v[70:73]
	v_mfma_i32_16x16x64_i8 v[130:133], v[170:173], v[178:181], v[130:133]
	v_mfma_i32_16x16x64_i8 v[130:133], v[174:177], v[182:185], v[130:133]
	v_mfma_i32_16x16x64_i8 v[110:113], v[170:173], v[186:189], v[110:113]
	v_mfma_i32_16x16x64_i8 v[110:113], v[174:177], v[190:193], v[110:113]
	v_mfma_i32_16x16x64_i8 v[82:85], v[170:173], v[200:203], v[82:85]
	v_mfma_i32_16x16x64_i8 v[82:85], v[174:177], v[204:207], v[82:85]
	v_mfma_i32_16x16x64_i8 v[66:69], v[170:173], v[208:211], v[66:69]
	v_mfma_i32_16x16x64_i8 v[66:69], v[174:177], v[212:215], v[66:69]
	s_barrier
	s_add_i32 s66, s66, s9
	s_mov_b32 m0, s66
	ds_read_b128 v[178:181], v161 offset:16384
	ds_read_b128 v[182:185], v161 offset:17408
	ds_read_b128 v[186:189], v161 offset:18432
	ds_read_b128 v[190:193], v161 offset:19456
	ds_read_b128 v[200:203], v161 offset:20480
	ds_read_b128 v[204:207], v161 offset:21504
	ds_read_b128 v[208:211], v161 offset:22528
	ds_read_b128 v[212:215], v161 offset:23552
	global_load_lds_dwordx4 v0, s[34:35]
	s_add_i32 m0, s66, 0x2000
	s_add_u32 s66, s34, 0x80000
	s_addc_u32 s67, s35, 0
	s_add_i32 s73, s73, s9
	global_load_lds_dwordx4 v146, s[34:35]
	s_mov_b32 m0, s73
	s_nop 0
	global_load_lds_dwordx4 v0, s[66:67]
	s_add_i32 m0, s73, 0x2000
	s_nop 0
	global_load_lds_dwordx4 v146, s[66:67]
	s_waitcnt vmcnt(6)
	s_waitcnt lgkmcnt(0)
	s_barrier
	v_mfma_i32_16x16x64_i8 v[62:65], v[90:93], v[178:181], v[62:65]
	v_mfma_i32_16x16x64_i8 v[62:65], v[94:97], v[182:185], v[62:65]
	v_mfma_i32_16x16x64_i8 v[46:49], v[90:93], v[186:189], v[46:49]
	v_mfma_i32_16x16x64_i8 v[46:49], v[94:97], v[190:193], v[46:49]
	v_mfma_i32_16x16x64_i8 v[30:33], v[90:93], v[200:203], v[30:33]
	v_mfma_i32_16x16x64_i8 v[30:33], v[94:97], v[204:207], v[30:33]
	v_mfma_i32_16x16x64_i8 v[14:17], v[90:93], v[208:211], v[14:17]
	v_mfma_i32_16x16x64_i8 v[14:17], v[94:97], v[212:215], v[14:17]
	v_mfma_i32_16x16x64_i8 v[58:61], v[106:109], v[178:181], v[58:61]
	v_mfma_i32_16x16x64_i8 v[58:61], v[114:117], v[182:185], v[58:61]
	v_mfma_i32_16x16x64_i8 v[42:45], v[106:109], v[186:189], v[42:45]
	v_mfma_i32_16x16x64_i8 v[42:45], v[114:117], v[190:193], v[42:45]
	v_mfma_i32_16x16x64_i8 v[26:29], v[106:109], v[200:203], v[26:29]
	v_mfma_i32_16x16x64_i8 v[26:29], v[114:117], v[204:207], v[26:29]
	v_mfma_i32_16x16x64_i8 v[10:13], v[106:109], v[208:211], v[10:13]
	v_mfma_i32_16x16x64_i8 v[10:13], v[114:117], v[212:215], v[10:13]
	v_mfma_i32_16x16x64_i8 v[54:57], v[162:165], v[178:181], v[54:57]
	v_mfma_i32_16x16x64_i8 v[54:57], v[166:169], v[182:185], v[54:57]
	v_mfma_i32_16x16x64_i8 v[38:41], v[162:165], v[186:189], v[38:41]
	v_mfma_i32_16x16x64_i8 v[38:41], v[166:169], v[190:193], v[38:41]
	v_mfma_i32_16x16x64_i8 v[22:25], v[162:165], v[200:203], v[22:25]
	v_mfma_i32_16x16x64_i8 v[22:25], v[166:169], v[204:207], v[22:25]
	v_mfma_i32_16x16x64_i8 v[6:9], v[162:165], v[208:211], v[6:9]
	v_mfma_i32_16x16x64_i8 v[6:9], v[166:169], v[212:215], v[6:9]
	v_mfma_i32_16x16x64_i8 v[50:53], v[170:173], v[178:181], v[50:53]
	v_mfma_i32_16x16x64_i8 v[50:53], v[174:177], v[182:185], v[50:53]
	v_mfma_i32_16x16x64_i8 v[34:37], v[170:173], v[186:189], v[34:37]
	v_mfma_i32_16x16x64_i8 v[34:37], v[174:177], v[190:193], v[34:37]
	v_mfma_i32_16x16x64_i8 v[18:21], v[170:173], v[200:203], v[18:21]
	v_mfma_i32_16x16x64_i8 v[18:21], v[174:177], v[204:207], v[18:21]
	v_mfma_i32_16x16x64_i8 v[2:5], v[170:173], v[208:211], v[2:5]
	v_mfma_i32_16x16x64_i8 v[2:5], v[174:177], v[212:215], v[2:5]
	s_barrier
	s_add_i32 s66, 0, 0x18000
	s_add_i32 s67, 0, 0x1c000
	v_add_u32_e32 v114, s66, v157
	v_add_u32_e32 v156, s67, v157
	ds_read_b128 v[90:93], v114
	ds_read_b128 v[94:97], v114 offset:1024
	ds_read_b128 v[106:109], v114 offset:2048
	ds_read_b128 v[114:117], v114 offset:3072
	ds_read_b128 v[162:165], v156
	ds_read_b128 v[166:169], v156 offset:1024
	ds_read_b128 v[170:173], v156 offset:2048
	ds_read_b128 v[174:177], v156 offset:3072
	s_mov_b32 m0, s14
	ds_read_b128 v[178:181], v161 offset:32768
	ds_read_b128 v[182:185], v161 offset:33792
	ds_read_b128 v[186:189], v161 offset:34816
	ds_read_b128 v[190:193], v161 offset:35840
	ds_read_b128 v[200:203], v161 offset:36864
	ds_read_b128 v[204:207], v161 offset:37888
	ds_read_b128 v[208:211], v161 offset:38912
	ds_read_b128 v[212:215], v161 offset:39936
	global_load_lds_dwordx4 v150, s[42:43]
	s_mov_b32 m0, s15
	s_nop 0
	global_load_lds_dwordx4 v148, s[42:43]
	s_add_u32 s42, s42, 0x80000
	s_addc_u32 s43, s43, 0
	s_mov_b32 m0, s46
	s_nop 0
	global_load_lds_dwordx4 v150, s[42:43]
	s_mov_b32 m0, s47
	s_nop 0
	global_load_lds_dwordx4 v148, s[42:43]
	s_waitcnt vmcnt(8)
	s_waitcnt lgkmcnt(0)
	s_barrier
	v_mfma_i32_16x16x64_i8 v[142:145], v[90:93], v[178:181], v[142:145]
	v_mfma_i32_16x16x64_i8 v[142:145], v[94:97], v[182:185], v[142:145]
	v_mfma_i32_16x16x64_i8 v[126:129], v[90:93], v[186:189], v[126:129]
	v_mfma_i32_16x16x64_i8 v[126:129], v[94:97], v[190:193], v[126:129]
	v_mfma_i32_16x16x64_i8 v[102:105], v[90:93], v[200:203], v[102:105]
	v_mfma_i32_16x16x64_i8 v[102:105], v[94:97], v[204:207], v[102:105]
	v_mfma_i32_16x16x64_i8 v[78:81], v[90:93], v[208:211], v[78:81]
	v_mfma_i32_16x16x64_i8 v[78:81], v[94:97], v[212:215], v[78:81]
	v_mfma_i32_16x16x64_i8 v[138:141], v[106:109], v[178:181], v[138:141]
	v_mfma_i32_16x16x64_i8 v[138:141], v[114:117], v[182:185], v[138:141]
	v_mfma_i32_16x16x64_i8 v[122:125], v[106:109], v[186:189], v[122:125]
	v_mfma_i32_16x16x64_i8 v[122:125], v[114:117], v[190:193], v[122:125]
	v_mfma_i32_16x16x64_i8 v[98:101], v[106:109], v[200:203], v[98:101]
	v_mfma_i32_16x16x64_i8 v[98:101], v[114:117], v[204:207], v[98:101]
	v_mfma_i32_16x16x64_i8 v[74:77], v[106:109], v[208:211], v[74:77]
	v_mfma_i32_16x16x64_i8 v[74:77], v[114:117], v[212:215], v[74:77]
	v_mfma_i32_16x16x64_i8 v[134:137], v[162:165], v[178:181], v[134:137]
	v_mfma_i32_16x16x64_i8 v[134:137], v[166:169], v[182:185], v[134:137]
	v_mfma_i32_16x16x64_i8 v[118:121], v[162:165], v[186:189], v[118:121]
	v_mfma_i32_16x16x64_i8 v[118:121], v[166:169], v[190:193], v[118:121]
	v_mfma_i32_16x16x64_i8 v[86:89], v[162:165], v[200:203], v[86:89]
	v_mfma_i32_16x16x64_i8 v[86:89], v[166:169], v[204:207], v[86:89]
	v_mfma_i32_16x16x64_i8 v[70:73], v[162:165], v[208:211], v[70:73]
	v_mfma_i32_16x16x64_i8 v[70:73], v[166:169], v[212:215], v[70:73]
	v_mfma_i32_16x16x64_i8 v[130:133], v[170:173], v[178:181], v[130:133]
	v_mfma_i32_16x16x64_i8 v[130:133], v[174:177], v[182:185], v[130:133]
	v_mfma_i32_16x16x64_i8 v[110:113], v[170:173], v[186:189], v[110:113]
	v_mfma_i32_16x16x64_i8 v[110:113], v[174:177], v[190:193], v[110:113]
	v_mfma_i32_16x16x64_i8 v[82:85], v[170:173], v[200:203], v[82:85]
	v_mfma_i32_16x16x64_i8 v[82:85], v[174:177], v[204:207], v[82:85]
	v_mfma_i32_16x16x64_i8 v[66:69], v[170:173], v[208:211], v[66:69]
	v_mfma_i32_16x16x64_i8 v[66:69], v[174:177], v[212:215], v[66:69]
	s_barrier
	s_add_u32 s98, s34, 0x80
	s_addc_u32 s99, s35, 0
	s_add_i32 s42, s66, s9
	s_mov_b32 m0, s42
	ds_read_b128 v[178:181], v161 offset:49152
	ds_read_b128 v[182:185], v161 offset:50176
	ds_read_b128 v[186:189], v161 offset:51200
	ds_read_b128 v[190:193], v161 offset:52224
	ds_read_b128 v[200:203], v161 offset:53248
	ds_read_b128 v[204:207], v161 offset:54272
	ds_read_b128 v[208:211], v161 offset:55296
	ds_read_b128 v[212:215], v161 offset:56320
	global_load_lds_dwordx4 v0, s[98:99]
	s_add_i32 m0, s42, 0x2000
	s_add_u32 s34, s34, 0x80080
	s_addc_u32 s35, s35, 0
	s_add_i32 s42, s67, s9
	global_load_lds_dwordx4 v146, s[98:99]
	s_mov_b32 m0, s42
	s_nop 0
	global_load_lds_dwordx4 v0, s[34:35]
	s_add_i32 m0, s42, 0x2000
	s_nop 0
	global_load_lds_dwordx4 v146, s[34:35]
	s_waitcnt vmcnt(6)
	s_waitcnt lgkmcnt(0)
	s_barrier
	v_mfma_i32_16x16x64_i8 v[62:65], v[90:93], v[178:181], v[62:65]
	v_mfma_i32_16x16x64_i8 v[62:65], v[94:97], v[182:185], v[62:65]
	v_mfma_i32_16x16x64_i8 v[46:49], v[90:93], v[186:189], v[46:49]
	v_mfma_i32_16x16x64_i8 v[46:49], v[94:97], v[190:193], v[46:49]
	v_mfma_i32_16x16x64_i8 v[30:33], v[90:93], v[200:203], v[30:33]
	v_mfma_i32_16x16x64_i8 v[30:33], v[94:97], v[204:207], v[30:33]
	v_mfma_i32_16x16x64_i8 v[14:17], v[90:93], v[208:211], v[14:17]
	v_mfma_i32_16x16x64_i8 v[14:17], v[94:97], v[212:215], v[14:17]
	v_mfma_i32_16x16x64_i8 v[58:61], v[106:109], v[178:181], v[58:61]
	v_mfma_i32_16x16x64_i8 v[58:61], v[114:117], v[182:185], v[58:61]
	v_mfma_i32_16x16x64_i8 v[42:45], v[106:109], v[186:189], v[42:45]
	v_mfma_i32_16x16x64_i8 v[42:45], v[114:117], v[190:193], v[42:45]
	s_add_i32 s57, s57, 2
	v_mfma_i32_16x16x64_i8 v[26:29], v[106:109], v[200:203], v[26:29]
	v_mfma_i32_16x16x64_i8 v[26:29], v[114:117], v[204:207], v[26:29]
	s_add_u32 s30, s30, 0x100
	s_addc_u32 s31, s31, 0
	v_mfma_i32_16x16x64_i8 v[10:13], v[106:109], v[208:211], v[10:13]
	v_mfma_i32_16x16x64_i8 v[10:13], v[114:117], v[212:215], v[10:13]
	s_add_u32 s55, s55, 0x100
	s_addc_u32 s56, s56, 0
	v_mfma_i32_16x16x64_i8 v[54:57], v[162:165], v[178:181], v[54:57]
	v_mfma_i32_16x16x64_i8 v[54:57], v[166:169], v[182:185], v[54:57]
	s_add_u32 s98, s30, 0xfff80000
	s_addc_u32 s99, s31, -1
	v_mfma_i32_16x16x64_i8 v[38:41], v[162:165], v[186:189], v[38:41]
	v_mfma_i32_16x16x64_i8 v[38:41], v[166:169], v[190:193], v[38:41]
	s_add_u32 s34, s30, 0xfff80080
	s_addc_u32 s35, s31, -1
	v_mfma_i32_16x16x64_i8 v[22:25], v[162:165], v[200:203], v[22:25]
	v_mfma_i32_16x16x64_i8 v[22:25], v[166:169], v[204:207], v[22:25]
	s_add_i32 s66, 0, 0x10000
	v_mfma_i32_16x16x64_i8 v[6:9], v[162:165], v[208:211], v[6:9]
	v_mfma_i32_16x16x64_i8 v[6:9], v[166:169], v[212:215], v[6:9]
	s_cmp_eq_u32 s57, 28
	s_cselect_b32 s43, s25, s35
	s_cselect_b32 s42, s53, s34
	s_cselect_b32 s35, s23, s56
	s_cselect_b32 s34, s54, s55
	v_mfma_i32_16x16x64_i8 v[50:53], v[170:173], v[178:181], v[50:53]
	v_mfma_i32_16x16x64_i8 v[50:53], v[174:177], v[182:185], v[50:53]
	s_add_i32 s73, 0, 0x14000
	v_mfma_i32_16x16x64_i8 v[34:37], v[170:173], v[186:189], v[34:37]
	v_mfma_i32_16x16x64_i8 v[34:37], v[174:177], v[190:193], v[34:37]
	s_cmp_gt_u32 s57, 29
	v_mfma_i32_16x16x64_i8 v[18:21], v[170:173], v[200:203], v[18:21]
	v_mfma_i32_16x16x64_i8 v[18:21], v[174:177], v[204:207], v[18:21]
	v_mfma_i32_16x16x64_i8 v[2:5], v[170:173], v[208:211], v[2:5]
	v_mfma_i32_16x16x64_i8 v[2:5], v[174:177], v[212:215], v[2:5]
	s_barrier
	s_cbranch_scc0 .Lkb_779
	s_and_b64 vcc, exec, s[20:21]
	s_mov_b32 s54, 0x5c401000
	s_cbranch_vccz .LBB0_782
	s_barrier

.Lkb_801:
	v_add_u32_e32 v156, s54, v141
	v_add_u32_e32 v172, s56, v141
	ds_read_b128 v[144:147], v156
	ds_read_b128 v[148:151], v156 offset:1024
	ds_read_b128 v[152:155], v156 offset:2048
	ds_read_b128 v[156:159], v156 offset:3072
	ds_read_b128 v[160:163], v172
	ds_read_b128 v[164:167], v172 offset:1024
	ds_read_b128 v[168:171], v172 offset:2048
	ds_read_b128 v[172:175], v172 offset:3072
	s_mov_b32 m0, s42
	ds_read_b128 v[176:179], v143
	ds_read_b128 v[180:183], v143 offset:1024
	ds_read_b128 v[184:187], v143 offset:2048
	ds_read_b128 v[188:191], v143 offset:3072
	ds_read_b128 v[192:195], v143 offset:4096
	ds_read_b128 v[200:203], v143 offset:5120
	ds_read_b128 v[204:207], v143 offset:6144
	ds_read_b128 v[208:211], v143 offset:7168
	global_load_lds_dwordx4 v134, s[98:99]
	s_mov_b32 m0, s43
	s_nop 0
	global_load_lds_dwordx4 v132, s[98:99]
	s_add_i32 m0, s14, 0xc000
	s_nop 0
	global_load_lds_dwordx4 v136, s[30:31]
	s_add_i32 m0, s14, 0xe000
	s_nop 0
	global_load_lds_dwordx4 v138, s[30:31]
	s_waitcnt vmcnt(8)
	s_waitcnt lgkmcnt(0)
	s_barrier
	v_mfma_f32_16x16x32_bf16 v[126:129], v[144:147], v[176:179], v[126:129]
	v_mfma_f32_16x16x32_bf16 v[126:129], v[148:151], v[180:183], v[126:129]
	v_mfma_f32_16x16x32_bf16 v[118:121], v[144:147], v[184:187], v[118:121]
	v_mfma_f32_16x16x32_bf16 v[118:121], v[148:151], v[188:191], v[118:121]
	v_mfma_f32_16x16x32_bf16 v[102:105], v[144:147], v[192:195], v[102:105]
	v_mfma_f32_16x16x32_bf16 v[102:105], v[148:151], v[200:203], v[102:105]
	v_mfma_f32_16x16x32_bf16 v[86:89], v[144:147], v[204:207], v[86:89]
	v_mfma_f32_16x16x32_bf16 v[86:89], v[148:151], v[208:211], v[86:89]
	v_mfma_f32_16x16x32_bf16 v[122:125], v[152:155], v[176:179], v[122:125]
	v_mfma_f32_16x16x32_bf16 v[122:125], v[156:159], v[180:183], v[122:125]
	v_mfma_f32_16x16x32_bf16 v[114:117], v[152:155], v[184:187], v[114:117]
	v_mfma_f32_16x16x32_bf16 v[114:117], v[156:159], v[188:191], v[114:117]
	v_mfma_f32_16x16x32_bf16 v[98:101], v[152:155], v[192:195], v[98:101]
	v_mfma_f32_16x16x32_bf16 v[98:101], v[156:159], v[200:203], v[98:101]
	v_mfma_f32_16x16x32_bf16 v[82:85], v[152:155], v[204:207], v[82:85]
	v_mfma_f32_16x16x32_bf16 v[82:85], v[156:159], v[208:211], v[82:85]
	v_mfma_f32_16x16x32_bf16 v[110:113], v[160:163], v[176:179], v[110:113]
	v_mfma_f32_16x16x32_bf16 v[110:113], v[164:167], v[180:183], v[110:113]
	v_mfma_f32_16x16x32_bf16 v[94:97], v[160:163], v[184:187], v[94:97]
	v_mfma_f32_16x16x32_bf16 v[94:97], v[164:167], v[188:191], v[94:97]
	v_mfma_f32_16x16x32_bf16 v[78:81], v[160:163], v[192:195], v[78:81]
	v_mfma_f32_16x16x32_bf16 v[78:81], v[164:167], v[200:203], v[78:81]
	v_mfma_f32_16x16x32_bf16 v[70:73], v[160:163], v[204:207], v[70:73]
	v_mfma_f32_16x16x32_bf16 v[70:73], v[164:167], v[208:211], v[70:73]
	v_mfma_f32_16x16x32_bf16 v[106:109], v[168:171], v[176:179], v[106:109]
	v_mfma_f32_16x16x32_bf16 v[106:109], v[172:175], v[180:183], v[106:109]
	v_mfma_f32_16x16x32_bf16 v[90:93], v[168:171], v[184:187], v[90:93]
	v_mfma_f32_16x16x32_bf16 v[90:93], v[172:175], v[188:191], v[90:93]
	v_mfma_f32_16x16x32_bf16 v[74:77], v[168:171], v[192:195], v[74:77]
	v_mfma_f32_16x16x32_bf16 v[74:77], v[172:175], v[200:203], v[74:77]
	v_mfma_f32_16x16x32_bf16 v[66:69], v[168:171], v[204:207], v[66:69]
	v_mfma_f32_16x16x32_bf16 v[66:69], v[172:175], v[208:211], v[66:69]
	s_barrier
	s_add_i32 s54, s54, s9
	s_mov_b32 m0, s54
	ds_read_b128 v[176:179], v143 offset:16384
	ds_read_b128 v[180:183], v143 offset:17408
	ds_read_b128 v[184:187], v143 offset:18432
	ds_read_b128 v[188:191], v143 offset:19456
	ds_read_b128 v[192:195], v143 offset:20480
	ds_read_b128 v[200:203], v143 offset:21504
	ds_read_b128 v[204:207], v143 offset:22528
	ds_read_b128 v[208:211], v143 offset:23552
	global_load_lds_dwordx4 v0, s[34:35]
	s_add_i32 m0, s54, 0x2000
	s_add_u32 s54, s34, 0x100000
	s_addc_u32 s55, s35, 0
	s_add_i32 s56, s56, s9
	global_load_lds_dwordx4 v130, s[34:35]
	s_mov_b32 m0, s56
	s_nop 0
	global_load_lds_dwordx4 v0, s[54:55]
	s_add_i32 m0, s56, 0x2000
	s_nop 0
	global_load_lds_dwordx4 v130, s[54:55]
	s_waitcnt vmcnt(6)
	s_waitcnt lgkmcnt(0)
	s_barrier
	v_mfma_f32_16x16x32_bf16 v[62:65], v[144:147], v[176:179], v[62:65]
	v_mfma_f32_16x16x32_bf16 v[62:65], v[148:151], v[180:183], v[62:65]
	v_mfma_f32_16x16x32_bf16 v[54:57], v[144:147], v[184:187], v[54:57]
	v_mfma_f32_16x16x32_bf16 v[54:57], v[148:151], v[188:191], v[54:57]
	v_mfma_f32_16x16x32_bf16 v[38:41], v[144:147], v[192:195], v[38:41]
	v_mfma_f32_16x16x32_bf16 v[38:41], v[148:151], v[200:203], v[38:41]
	v_mfma_f32_16x16x32_bf16 v[22:25], v[144:147], v[204:207], v[22:25]
	v_mfma_f32_16x16x32_bf16 v[22:25], v[148:151], v[208:211], v[22:25]
	v_mfma_f32_16x16x32_bf16 v[58:61], v[152:155], v[176:179], v[58:61]
	v_mfma_f32_16x16x32_bf16 v[58:61], v[156:159], v[180:183], v[58:61]
	v_mfma_f32_16x16x32_bf16 v[50:53], v[152:155], v[184:187], v[50:53]
	v_mfma_f32_16x16x32_bf16 v[50:53], v[156:159], v[188:191], v[50:53]
	v_mfma_f32_16x16x32_bf16 v[34:37], v[152:155], v[192:195], v[34:37]
	v_mfma_f32_16x16x32_bf16 v[34:37], v[156:159], v[200:203], v[34:37]
	v_mfma_f32_16x16x32_bf16 v[18:21], v[152:155], v[204:207], v[18:21]
	v_mfma_f32_16x16x32_bf16 v[18:21], v[156:159], v[208:211], v[18:21]
	v_mfma_f32_16x16x32_bf16 v[46:49], v[160:163], v[176:179], v[46:49]
	v_mfma_f32_16x16x32_bf16 v[46:49], v[164:167], v[180:183], v[46:49]
	v_mfma_f32_16x16x32_bf16 v[30:33], v[160:163], v[184:187], v[30:33]
	v_mfma_f32_16x16x32_bf16 v[30:33], v[164:167], v[188:191], v[30:33]
	v_mfma_f32_16x16x32_bf16 v[14:17], v[160:163], v[192:195], v[14:17]
	v_mfma_f32_16x16x32_bf16 v[14:17], v[164:167], v[200:203], v[14:17]
	v_mfma_f32_16x16x32_bf16 v[6:9], v[160:163], v[204:207], v[6:9]
	v_mfma_f32_16x16x32_bf16 v[6:9], v[164:167], v[208:211], v[6:9]
	v_mfma_f32_16x16x32_bf16 v[42:45], v[168:171], v[176:179], v[42:45]
	v_mfma_f32_16x16x32_bf16 v[42:45], v[172:175], v[180:183], v[42:45]
	v_mfma_f32_16x16x32_bf16 v[26:29], v[168:171], v[184:187], v[26:29]
	v_mfma_f32_16x16x32_bf16 v[26:29], v[172:175], v[188:191], v[26:29]
	v_mfma_f32_16x16x32_bf16 v[10:13], v[168:171], v[192:195], v[10:13]
	v_mfma_f32_16x16x32_bf16 v[10:13], v[172:175], v[200:203], v[10:13]
	v_mfma_f32_16x16x32_bf16 v[2:5], v[168:171], v[204:207], v[2:5]
	v_mfma_f32_16x16x32_bf16 v[2:5], v[172:175], v[208:211], v[2:5]
	s_barrier
	s_add_i32 s54, 0, 0x18000
	s_add_i32 s55, 0, 0x1c000
	v_add_u32_e32 v156, s54, v141
	v_add_u32_e32 v172, s55, v141
	ds_read_b128 v[144:147], v156
	ds_read_b128 v[148:151], v156 offset:1024
	ds_read_b128 v[152:155], v156 offset:2048
	ds_read_b128 v[156:159], v156 offset:3072
	ds_read_b128 v[160:163], v172
	ds_read_b128 v[164:167], v172 offset:1024
	ds_read_b128 v[168:171], v172 offset:2048
	ds_read_b128 v[172:175], v172 offset:3072
	s_mov_b32 m0, s14
	ds_read_b128 v[176:179], v143 offset:32768
	ds_read_b128 v[180:183], v143 offset:33792
	ds_read_b128 v[184:187], v143 offset:34816
	ds_read_b128 v[188:191], v143 offset:35840
	ds_read_b128 v[192:195], v143 offset:36864
	ds_read_b128 v[200:203], v143 offset:37888
	ds_read_b128 v[204:207], v143 offset:38912
	ds_read_b128 v[208:211], v143 offset:39936
	global_load_lds_dwordx4 v134, s[40:41]
	s_mov_b32 m0, s15
	s_nop 0
	global_load_lds_dwordx4 v132, s[40:41]
	s_add_u32 s40, s40, 0x100000
	s_addc_u32 s41, s41, 0
	s_mov_b32 m0, s18
	s_nop 0
	global_load_lds_dwordx4 v134, s[40:41]
	s_mov_b32 m0, s19
	s_nop 0
	global_load_lds_dwordx4 v132, s[40:41]
	s_waitcnt vmcnt(8)
	s_waitcnt lgkmcnt(0)
	s_barrier
	v_mfma_f32_16x16x32_bf16 v[126:129], v[144:147], v[176:179], v[126:129]
	v_mfma_f32_16x16x32_bf16 v[126:129], v[148:151], v[180:183], v[126:129]
	v_mfma_f32_16x16x32_bf16 v[118:121], v[144:147], v[184:187], v[118:121]
	v_mfma_f32_16x16x32_bf16 v[118:121], v[148:151], v[188:191], v[118:121]
	v_mfma_f32_16x16x32_bf16 v[102:105], v[144:147], v[192:195], v[102:105]
	v_mfma_f32_16x16x32_bf16 v[102:105], v[148:151], v[200:203], v[102:105]
	v_mfma_f32_16x16x32_bf16 v[86:89], v[144:147], v[204:207], v[86:89]
	v_mfma_f32_16x16x32_bf16 v[86:89], v[148:151], v[208:211], v[86:89]
	v_mfma_f32_16x16x32_bf16 v[122:125], v[152:155], v[176:179], v[122:125]
	v_mfma_f32_16x16x32_bf16 v[122:125], v[156:159], v[180:183], v[122:125]
	v_mfma_f32_16x16x32_bf16 v[114:117], v[152:155], v[184:187], v[114:117]
	v_mfma_f32_16x16x32_bf16 v[114:117], v[156:159], v[188:191], v[114:117]
	v_mfma_f32_16x16x32_bf16 v[98:101], v[152:155], v[192:195], v[98:101]
	v_mfma_f32_16x16x32_bf16 v[98:101], v[156:159], v[200:203], v[98:101]
	v_mfma_f32_16x16x32_bf16 v[82:85], v[152:155], v[204:207], v[82:85]
	v_mfma_f32_16x16x32_bf16 v[82:85], v[156:159], v[208:211], v[82:85]
	v_mfma_f32_16x16x32_bf16 v[110:113], v[160:163], v[176:179], v[110:113]
	v_mfma_f32_16x16x32_bf16 v[110:113], v[164:167], v[180:183], v[110:113]
	v_mfma_f32_16x16x32_bf16 v[94:97], v[160:163], v[184:187], v[94:97]
	v_mfma_f32_16x16x32_bf16 v[94:97], v[164:167], v[188:191], v[94:97]
	v_mfma_f32_16x16x32_bf16 v[78:81], v[160:163], v[192:195], v[78:81]
	v_mfma_f32_16x16x32_bf16 v[78:81], v[164:167], v[200:203], v[78:81]
	v_mfma_f32_16x16x32_bf16 v[70:73], v[160:163], v[204:207], v[70:73]
	v_mfma_f32_16x16x32_bf16 v[70:73], v[164:167], v[208:211], v[70:73]
	v_mfma_f32_16x16x32_bf16 v[106:109], v[168:171], v[176:179], v[106:109]
	v_mfma_f32_16x16x32_bf16 v[106:109], v[172:175], v[180:183], v[106:109]
	v_mfma_f32_16x16x32_bf16 v[90:93], v[168:171], v[184:187], v[90:93]
	v_mfma_f32_16x16x32_bf16 v[90:93], v[172:175], v[188:191], v[90:93]
	v_mfma_f32_16x16x32_bf16 v[74:77], v[168:171], v[192:195], v[74:77]
	v_mfma_f32_16x16x32_bf16 v[74:77], v[172:175], v[200:203], v[74:77]
	v_mfma_f32_16x16x32_bf16 v[66:69], v[168:171], v[204:207], v[66:69]
	v_mfma_f32_16x16x32_bf16 v[66:69], v[172:175], v[208:211], v[66:69]
	s_barrier
	s_add_u32 s98, s34, 0x80
	s_addc_u32 s99, s35, 0
	s_add_i32 s40, s54, s9
	s_mov_b32 m0, s40
	ds_read_b128 v[176:179], v143 offset:49152
	ds_read_b128 v[180:183], v143 offset:50176
	ds_read_b128 v[184:187], v143 offset:51200
	ds_read_b128 v[188:191], v143 offset:52224
	ds_read_b128 v[192:195], v143 offset:53248
	ds_read_b128 v[200:203], v143 offset:54272
	ds_read_b128 v[204:207], v143 offset:55296
	ds_read_b128 v[208:211], v143 offset:56320
	global_load_lds_dwordx4 v0, s[98:99]
	s_add_i32 m0, s40, 0x2000
	s_add_u32 s34, s34, 0x100080
	s_addc_u32 s35, s35, 0
	s_add_i32 s40, s55, s9
	global_load_lds_dwordx4 v130, s[98:99]
	s_mov_b32 m0, s40
	s_nop 0
	global_load_lds_dwordx4 v0, s[34:35]
	s_add_i32 m0, s40, 0x2000
	s_nop 0
	global_load_lds_dwordx4 v130, s[34:35]
	s_waitcnt vmcnt(6)
	s_waitcnt lgkmcnt(0)
	s_barrier
	v_mfma_f32_16x16x32_bf16 v[62:65], v[144:147], v[176:179], v[62:65]
	v_mfma_f32_16x16x32_bf16 v[62:65], v[148:151], v[180:183], v[62:65]
	v_mfma_f32_16x16x32_bf16 v[54:57], v[144:147], v[184:187], v[54:57]
	v_mfma_f32_16x16x32_bf16 v[54:57], v[148:151], v[188:191], v[54:57]
	v_mfma_f32_16x16x32_bf16 v[38:41], v[144:147], v[192:195], v[38:41]
	v_mfma_f32_16x16x32_bf16 v[38:41], v[148:151], v[200:203], v[38:41]
	v_mfma_f32_16x16x32_bf16 v[22:25], v[144:147], v[204:207], v[22:25]
	v_mfma_f32_16x16x32_bf16 v[22:25], v[148:151], v[208:211], v[22:25]
	v_mfma_f32_16x16x32_bf16 v[58:61], v[152:155], v[176:179], v[58:61]
	v_mfma_f32_16x16x32_bf16 v[58:61], v[156:159], v[180:183], v[58:61]
	v_mfma_f32_16x16x32_bf16 v[50:53], v[152:155], v[184:187], v[50:53]
	v_mfma_f32_16x16x32_bf16 v[50:53], v[156:159], v[188:191], v[50:53]
	s_add_i32 s53, s53, 2
	v_mfma_f32_16x16x32_bf16 v[34:37], v[152:155], v[192:195], v[34:37]
	v_mfma_f32_16x16x32_bf16 v[34:37], v[156:159], v[200:203], v[34:37]
	s_add_u32 s30, s30, 0x100
	s_addc_u32 s31, s31, 0
	v_mfma_f32_16x16x32_bf16 v[18:21], v[152:155], v[204:207], v[18:21]
	v_mfma_f32_16x16x32_bf16 v[18:21], v[156:159], v[208:211], v[18:21]
	s_add_u32 s51, s51, 0x100
	s_addc_u32 s52, s52, 0
	v_mfma_f32_16x16x32_bf16 v[46:49], v[160:163], v[176:179], v[46:49]
	v_mfma_f32_16x16x32_bf16 v[46:49], v[164:167], v[180:183], v[46:49]
	s_add_u32 s98, s30, 0xfff00000
	s_addc_u32 s99, s31, -1
	v_mfma_f32_16x16x32_bf16 v[30:33], v[160:163], v[184:187], v[30:33]
	v_mfma_f32_16x16x32_bf16 v[30:33], v[164:167], v[188:191], v[30:33]
	s_add_u32 s34, s30, 0xfff00080
	s_addc_u32 s35, s31, -1
	v_mfma_f32_16x16x32_bf16 v[14:17], v[160:163], v[192:195], v[14:17]
	v_mfma_f32_16x16x32_bf16 v[14:17], v[164:167], v[200:203], v[14:17]
	s_add_i32 s54, 0, 0x10000
	v_mfma_f32_16x16x32_bf16 v[6:9], v[160:163], v[204:207], v[6:9]
	v_mfma_f32_16x16x32_bf16 v[6:9], v[164:167], v[208:211], v[6:9]
	s_cmp_eq_u32 s53, 60
	s_cselect_b32 s41, s25, s35
	s_cselect_b32 s40, s49, s34
	s_cselect_b32 s35, s23, s52
	s_cselect_b32 s34, s50, s51
	v_mfma_f32_16x16x32_bf16 v[42:45], v[168:171], v[176:179], v[42:45]
	v_mfma_f32_16x16x32_bf16 v[42:45], v[172:175], v[180:183], v[42:45]
	s_add_i32 s56, 0, 0x14000
	v_mfma_f32_16x16x32_bf16 v[26:29], v[168:171], v[184:187], v[26:29]
	v_mfma_f32_16x16x32_bf16 v[26:29], v[172:175], v[188:191], v[26:29]
	s_cmp_gt_u32 s53, 61
	v_mfma_f32_16x16x32_bf16 v[10:13], v[168:171], v[192:195], v[10:13]
	v_mfma_f32_16x16x32_bf16 v[10:13], v[172:175], v[200:203], v[10:13]
	v_mfma_f32_16x16x32_bf16 v[2:5], v[168:171], v[204:207], v[2:5]
	v_mfma_f32_16x16x32_bf16 v[2:5], v[172:175], v[208:211], v[2:5]
	s_barrier
	s_cbranch_scc0 .Lkb_801
	s_and_b64 vcc, exec, s[20:21]
	s_cbranch_vccz .LBB0_804
	s_barrier
